# v21 + next-tile shortcut (pm same / pn+4 or pm+4) replacing the per-unit divide chain when gridDim.x == 256
# speedup vs baseline: 1.0024x; 1.0024x over previous
;     __host__ __device__ bool next(int i, Unit& u) const {
;         const long L = (long)i * G + c; if (L >= nwg) return false;
;         int wgid = (int)L; { const int q = nwg / NXCD, r = nwg % NXCD, xcd = wgid % NXCD, off = wgid / NXCD; wgid = (xcd < r ? xcd * (q + 1) : r * (q + 1) + (xcd - r) * q) + off; }
;         const int nig = WGM * nN, gid = wgid / nig, fm = gid * WGM, gsz = (nM - fm) < WGM ? (nM - fm) : WGM;
;         if (pn_fast) { u.pm = fm + (wgid % nig) / nN; u.pn = (wgid % nig) % nN; } else { u.pm = fm + ((wgid % nig) % gsz); u.pn = (wgid % nig) / gsz; }
; template <class Epi, class Sched, bool ALIGN_EPI = false, bool SP2 = false, bool F16 = false>
; __device__ __forceinline__ void gemm_phase(PG8_LAS unsigned char* lds, const Gemm g, const Sched& S, const Epi& E) {
;     ...
;         const bool has_next = S.next(ui + 1, nxt);
;         const char* nA = has_next ? (const char*)g.A + (size_t)nxt.pm * tstepA : cA; const char* nB = has_next ? (const char*)g.Bt + (size_t)nxt.pn * tstepB : cB;
.LBB0_299:
	s_add_i32 s61, s61, 1
	v_readlane_b32 s36, v251, 50
	s_mul_i32 s36, s61, s36
	s_mul_hi_u32 s37, s61, s91
	s_add_i32 s37, s37, s36
	s_mul_i32 s36, s61, s91
	v_readlane_b32 s38, v251, 0
	s_add_u32 s36, s36, s38
	v_readlane_b32 s38, v251, 9
	s_addc_u32 s37, s37, s38
	v_mov_b64_e32 v[2:3], s[6:7]
	v_cmp_ge_i64_e32 vcc, s[36:37], v[2:3]
	v_cmp_lt_i64_e64 s[38:39], s[36:37], v[2:3]
	s_cbranch_vccnz .LBB0_304
	s_cmp_lg_u32 s91, 0x100
	s_cbranch_scc1 .Lsn_gu_slow
	s_mov_b32 s75, s23
	s_add_i32 s73, s78, 4
	s_branch .LBB0_304
.Lsn_gu_slow:
	s_ashr_i32 s37, s36, 31
	s_lshr_b32 s37, s37, 29
	s_add_i32 s37, s36, s37
	s_ashr_i32 s46, s37, 3
	s_and_b32 s37, s37, -8
	s_sub_i32 s36, s36, s37
	s_lshr_b32 s37, s36, 31
	s_add_i32 s37, s30, s37
	s_mul_i32 s82, s37, s36
	s_add_i32 s82, s82, s46
	s_abs_i32 s36, s82
	s_mul_hi_u32 s37, s36, s3
	s_mul_i32 s46, s37, s31
	s_sub_i32 s80, s36, s46
	s_ashr_i32 s47, s82, 31
	s_add_i32 s36, s37, 1
	s_sub_i32 s81, s80, s31
	s_cmp_ge_u32 s80, s31
	s_cselect_b32 s36, s36, s37
	s_cselect_b32 s37, s81, s80
	s_add_i32 s46, s36, 1
	s_cmp_ge_u32 s37, s31
	s_cselect_b32 s36, s46, s36
	s_xor_b32 s36, s36, s47
	v_readlane_b32 s42, v248, 27
	s_sub_i32 s83, s36, s47
	v_readlane_b32 s43, v248, 28
	s_lshl_b32 s46, s83, 3
	s_mov_b64 s[36:37], -1
	s_and_b64 vcc, exec, s[42:43]
	s_cbranch_vccz .LBB0_302
	v_readlane_b32 s36, v248, 26
	s_sub_i32 s36, s36, s46
	s_min_i32 s36, s36, 8
	s_abs_i32 s37, s36
	v_cvt_f32_u32_e32 v2, s37
	s_mul_i32 s83, s83, s31
	s_sub_i32 s75, s82, s83
	s_sub_i32 s83, 0, s37
	v_rcp_iflag_f32_e32 v2, v2
	s_abs_i32 s82, s75
	s_xor_b32 s73, s75, s36
	s_ashr_i32 s73, s73, 31
	v_mul_f32_e32 v2, 0x4f7ffffe, v2
	v_cvt_u32_f32_e32 v2, v2
	s_nop 0
	v_readfirstlane_b32 s94, v2
	s_mul_i32 s83, s83, s94
	s_mul_hi_u32 s83, s94, s83
	s_add_i32 s94, s94, s83
	s_mul_hi_u32 s83, s82, s94
	s_mul_i32 s94, s83, s37
	s_sub_i32 s82, s82, s94
	s_add_i32 s95, s83, 1
	s_sub_i32 s94, s82, s37
	s_cmp_ge_u32 s82, s37
	s_cselect_b32 s83, s95, s83
	s_cselect_b32 s82, s94, s82
	s_add_i32 s94, s83, 1
	s_cmp_ge_u32 s82, s37
	s_cselect_b32 s37, s94, s83
	s_xor_b32 s37, s37, s73
	s_sub_i32 s73, s37, s73
	s_mul_i32 s36, s73, s36
	s_sub_i32 s36, s75, s36
	s_add_i32 s75, s36, s46
	s_mov_b64 s[36:37], 0

;     __host__ __device__ bool next(int i, Unit& u) const {
;         const long L = (long)i * G + c; if (L >= nwg) return false;
;         int wgid = (int)L; { const int q = nwg / NXCD, r = nwg % NXCD, xcd = wgid % NXCD, off = wgid / NXCD; wgid = (xcd < r ? xcd * (q + 1) : r * (q + 1) + (xcd - r) * q) + off; }
;         const int nig = WGM * nN, gid = wgid / nig, fm = gid * WGM, gsz = (nM - fm) < WGM ? (nM - fm) : WGM;
;         if (pn_fast) { u.pm = fm + (wgid % nig) / nN; u.pn = (wgid % nig) % nN; } else { u.pm = fm + ((wgid % nig) % gsz); u.pn = (wgid % nig) / gsz; }
; template <class Epi, class Sched, bool ALIGN_EPI = false, bool SP2 = false, bool F16 = false>
; __device__ __forceinline__ void gemm_phase(PG8_LAS unsigned char* lds, const Gemm g, const Sched& S, const Epi& E) {
;     ...
;         const bool has_next = S.next(ui + 1, nxt);
;         const char* nA = has_next ? (const char*)g.A + (size_t)nxt.pm * tstepA : cA; const char* nB = has_next ? (const char*)g.Bt + (size_t)nxt.pn * tstepB : cB;
.LBB0_334:
	s_add_i32 s59, s59, 1
	v_readlane_b32 s38, v251, 50
	s_mul_i32 s38, s59, s38
	s_mul_hi_u32 s39, s59, s91
	s_add_i32 s39, s39, s38
	s_mul_i32 s38, s59, s91
	v_readlane_b32 s40, v251, 0
	s_add_u32 s38, s38, s40
	v_readlane_b32 s40, v251, 9
	s_addc_u32 s39, s39, s40
	s_waitcnt lgkmcnt(0)
	v_mov_b64_e32 v[2:3], s[6:7]
	v_cmp_ge_i64_e32 vcc, s[38:39], v[2:3]
	v_cmp_lt_i64_e64 s[40:41], s[38:39], v[2:3]
	s_cbranch_vccnz .LBB0_339
	s_cmp_lg_u32 s91, 0x100
	s_cbranch_scc1 .Lsn_rs_slow
	s_add_i32 s75, s78, 4
	s_mov_b32 s73, s24
	s_branch .LBB0_339
.Lsn_rs_slow:
	s_ashr_i32 s39, s38, 31
	s_lshr_b32 s39, s39, 29
	s_add_i32 s39, s38, s39
	s_ashr_i32 s46, s39, 3
	s_and_b32 s39, s39, -8
	s_sub_i32 s38, s38, s39
	s_lshr_b32 s39, s38, 31
	s_add_i32 s39, s30, s39
	s_mul_i32 s81, s39, s38
	s_add_i32 s81, s81, s46
	s_abs_i32 s38, s81
	s_mul_hi_u32 s39, s38, s61
	s_mul_i32 s46, s39, s31
	s_sub_i32 s79, s38, s46
	s_ashr_i32 s47, s81, 31
	s_add_i32 s38, s39, 1
	s_sub_i32 s80, s79, s31
	s_cmp_ge_u32 s79, s31
	s_cselect_b32 s38, s38, s39
	s_cselect_b32 s39, s80, s79
	s_add_i32 s46, s38, 1
	s_cmp_ge_u32 s39, s31
	s_cselect_b32 s38, s46, s38
	s_xor_b32 s38, s38, s47
	v_readlane_b32 s42, v248, 27
	s_sub_i32 s82, s38, s47
	v_readlane_b32 s43, v248, 28
	s_lshl_b32 s46, s82, 3
	s_mov_b64 s[38:39], -1
	s_and_b64 vcc, exec, s[42:43]
	s_cbranch_vccz .LBB0_337
	v_readlane_b32 s38, v248, 26
	s_sub_i32 s38, s38, s46
	s_min_i32 s38, s38, 8
	s_abs_i32 s39, s38
	v_cvt_f32_u32_e32 v2, s39
	s_mul_i32 s82, s82, s31
	s_sub_i32 s75, s81, s82
	s_sub_i32 s82, 0, s39
	v_rcp_iflag_f32_e32 v2, v2
	s_abs_i32 s81, s75
	s_xor_b32 s73, s75, s38
	s_ashr_i32 s73, s73, 31
	v_mul_f32_e32 v2, 0x4f7ffffe, v2
	v_cvt_u32_f32_e32 v2, v2
	s_nop 0
	v_readfirstlane_b32 s83, v2
	s_mul_i32 s82, s82, s83
	s_mul_hi_u32 s82, s83, s82
	s_add_i32 s83, s83, s82
	s_mul_hi_u32 s82, s81, s83
	s_mul_i32 s83, s82, s39
	s_sub_i32 s81, s81, s83
	s_add_i32 s94, s82, 1
	s_sub_i32 s83, s81, s39
	s_cmp_ge_u32 s81, s39
	s_cselect_b32 s82, s94, s82
	s_cselect_b32 s81, s83, s81
	s_add_i32 s83, s82, 1
	s_cmp_ge_u32 s81, s39
	s_cselect_b32 s39, s83, s82
	s_xor_b32 s39, s39, s73
	s_sub_i32 s73, s39, s73
	s_mul_i32 s38, s73, s38
	s_sub_i32 s38, s75, s38
	s_add_i32 s75, s38, s46
	s_mov_b64 s[38:39], 0

;     __host__ __device__ bool next(int i, Unit& u) const {
;         const long L = (long)i * G + c; if (L >= nwg) return false;
;         int wgid = (int)L; { const int q = nwg / NXCD, r = nwg % NXCD, xcd = wgid % NXCD, off = wgid / NXCD; wgid = (xcd < r ? xcd * (q + 1) : r * (q + 1) + (xcd - r) * q) + off; }
;         const int nig = WGM * nN, gid = wgid / nig, fm = gid * WGM, gsz = (nM - fm) < WGM ? (nM - fm) : WGM;
;         if (pn_fast) { u.pm = fm + (wgid % nig) / nN; u.pn = (wgid % nig) % nN; } else { u.pm = fm + ((wgid % nig) % gsz); u.pn = (wgid % nig) / gsz; }
; template <class Epi, class Sched, bool ALIGN_EPI = false, bool SP2 = false, bool F16 = false>
; __device__ __forceinline__ void gemm_phase(PG8_LAS unsigned char* lds, const Gemm g, const Sched& S, const Epi& E) {
;     ...
;         const bool has_next = S.next(ui + 1, nxt);
;         const char* nA = has_next ? (const char*)g.A + (size_t)nxt.pm * tstepA : cA; const char* nB = has_next ? (const char*)g.Bt + (size_t)nxt.pn * tstepB : cB;
.LBB0_387:
	s_add_i32 s18, s18, 1
	v_readlane_b32 s13, v251, 50
	s_mul_i32 s13, s18, s13
	s_mul_hi_u32 s24, s18, s91
	s_add_i32 s24, s24, s13
	s_mul_i32 s13, s18, s91
	v_readlane_b32 s44, v251, 0
	s_add_u32 s44, s13, s44
	v_readlane_b32 s13, v251, 9
	s_addc_u32 s45, s24, s13
	s_waitcnt lgkmcnt(0)
	v_mov_b64_e32 v[2:3], s[6:7]
	v_cmp_ge_i64_e32 vcc, s[44:45], v[2:3]
	v_cmp_lt_i64_e64 s[46:47], s[44:45], v[2:3]
	s_cbranch_vccnz .LBB0_392
	s_cmp_lg_u32 s91, 0x100
	s_cbranch_scc1 .Lsn_bf_slow
	s_mov_b32 s3, s12
	s_add_i32 s59, s33, 4
	s_branch .LBB0_392
.Lsn_bf_slow:
	s_ashr_i32 s3, s44, 31
	s_lshr_b32 s3, s3, 29
	s_add_i32 s3, s44, s3
	s_ashr_i32 s13, s3, 3
	s_and_b32 s3, s3, -8
	s_sub_i32 s3, s44, s3
	s_lshr_b32 s24, s3, 31
	s_add_i32 s24, s30, s24
	s_mul_i32 s54, s24, s3
	s_add_i32 s54, s54, s13
	s_abs_i32 s3, s54
	v_readlane_b32 s13, v248, 33
	s_mul_hi_u32 s13, s3, s13
	s_mul_i32 s44, s13, s31
	s_sub_i32 s52, s3, s44
	s_ashr_i32 s24, s54, 31
	s_add_i32 s3, s13, 1
	s_sub_i32 s53, s52, s31
	s_cmp_ge_u32 s52, s31
	s_cselect_b32 s3, s3, s13
	s_cselect_b32 s13, s53, s52
	s_add_i32 s44, s3, 1
	s_cmp_ge_u32 s13, s31
	s_cselect_b32 s3, s44, s3
	s_xor_b32 s3, s3, s24
	v_readlane_b32 s94, v248, 27
	s_sub_i32 s55, s3, s24
	v_readlane_b32 s95, v248, 28
	s_lshl_b32 s13, s55, 3
	s_mov_b64 s[44:45], -1
	s_and_b64 vcc, exec, s[94:95]
	s_cbranch_vccz .LBB0_390
	v_readlane_b32 s3, v248, 26
	s_sub_i32 s3, s3, s13
	s_min_i32 s3, s3, 8
	s_abs_i32 s44, s3
	v_cvt_f32_u32_e32 v2, s44
	s_sub_i32 s59, 0, s44
	s_mul_i32 s55, s55, s31
	s_sub_i32 s45, s54, s55
	v_rcp_iflag_f32_e32 v2, v2
	s_abs_i32 s55, s45
	s_xor_b32 s54, s45, s3
	s_ashr_i32 s54, s54, 31
	v_mul_f32_e32 v2, 0x4f7ffffe, v2
	v_cvt_u32_f32_e32 v2, v2
	s_nop 0
	v_readfirstlane_b32 s94, v2
	s_mul_i32 s59, s59, s94
	s_mul_hi_u32 s59, s94, s59
	s_add_i32 s94, s94, s59
	s_mul_hi_u32 s59, s55, s94
	s_mul_i32 s94, s59, s44
	s_sub_i32 s55, s55, s94
	s_add_i32 s95, s59, 1
	s_sub_i32 s94, s55, s44
	s_cmp_ge_u32 s55, s44
	s_cselect_b32 s59, s95, s59
	s_cselect_b32 s55, s94, s55
	s_add_i32 s94, s59, 1
	s_cmp_ge_u32 s55, s44
	s_cselect_b32 s44, s94, s59
	s_xor_b32 s44, s44, s54
	s_sub_i32 s59, s44, s54
	s_mul_i32 s3, s59, s3
	s_sub_i32 s3, s45, s3
	s_add_i32 s3, s3, s13
	s_mov_b64 s[44:45], 0

;     __host__ __device__ bool next(int i, Unit& u) const {
;         const long L = (long)i * G + c; if (L >= nwg) return false;
;         int wgid = (int)L; { const int q = nwg / NXCD, r = nwg % NXCD, xcd = wgid % NXCD, off = wgid / NXCD; wgid = (xcd < r ? xcd * (q + 1) : r * (q + 1) + (xcd - r) * q) + off; }
;         const int nig = WGM * nN, gid = wgid / nig, fm = gid * WGM, gsz = (nM - fm) < WGM ? (nM - fm) : WGM;
;         if (pn_fast) { u.pm = fm + (wgid % nig) / nN; u.pn = (wgid % nig) % nN; } else { u.pm = fm + ((wgid % nig) % gsz); u.pn = (wgid % nig) / gsz; }
; template <class Epi, class Sched, bool ALIGN_EPI = false, bool SP2 = false, bool F16 = false>
; __device__ __forceinline__ void gemm_phase(PG8_LAS unsigned char* lds, const Gemm g, const Sched& S, const Epi& E) {
;     ...
;         const bool has_next = S.next(ui + 1, nxt);
;         const char* nA = has_next ? (const char*)g.A + (size_t)nxt.pm * tstepA : cA; const char* nB = has_next ? (const char*)g.Bt + (size_t)nxt.pn * tstepB : cB;
.LBB0_553:
	s_add_i32 s59, s59, 1
	v_readlane_b32 s24, v251, 50
	s_mul_i32 s24, s59, s24
	s_mul_hi_u32 s42, s59, s91
	s_add_i32 s24, s42, s24
	s_mul_i32 s42, s59, s91
	v_readlane_b32 s43, v251, 0
	s_add_u32 s42, s42, s43
	v_readlane_b32 s43, v251, 9
	s_addc_u32 s43, s24, s43
	s_waitcnt lgkmcnt(0)
	v_mov_b64_e32 v[2:3], s[6:7]
	v_cmp_ge_i64_e32 vcc, s[42:43], v[2:3]
	v_cmp_lt_i64_e64 s[44:45], s[42:43], v[2:3]
	s_cbranch_vccnz .LBB0_558
	s_cmp_lg_u32 s91, 0x100
	s_cbranch_scc1 .Lsn_bh_slow
	s_mov_b32 s33, s13
	s_add_i32 s12, s3, 4
	s_branch .LBB0_558
.Lsn_bh_slow:
	s_ashr_i32 s12, s42, 31
	s_lshr_b32 s12, s12, 29
	s_add_i32 s12, s42, s12
	s_ashr_i32 s24, s12, 3
	s_and_b32 s12, s12, -8
	s_sub_i32 s12, s42, s12
	s_lshr_b32 s33, s12, 31
	s_add_i32 s33, s30, s33
	s_mul_i32 s79, s33, s12
	s_add_i32 s79, s79, s24
	s_abs_i32 s12, s79
	v_readlane_b32 s24, v248, 2
	s_mul_hi_u32 s24, s12, s24
	s_mul_i32 s33, s24, s31
	s_sub_i32 s55, s12, s33
	s_ashr_i32 s54, s79, 31
	s_add_i32 s12, s24, 1
	s_sub_i32 s78, s55, s31
	s_cmp_ge_u32 s55, s31
	s_cselect_b32 s12, s12, s24
	s_cselect_b32 s24, s78, s55
	s_add_i32 s33, s12, 1
	s_cmp_ge_u32 s24, s31
	s_cselect_b32 s12, s33, s12
	s_xor_b32 s12, s12, s54
	v_readlane_b32 s94, v248, 27
	s_sub_i32 s82, s12, s54
	v_readlane_b32 s95, v248, 28
	s_lshl_b32 s24, s82, 3
	s_mov_b64 s[42:43], -1
	s_and_b64 vcc, exec, s[94:95]
	s_cbranch_vccz .LBB0_556
	v_readlane_b32 s12, v248, 26
	s_sub_i32 s12, s12, s24
	s_min_i32 s33, s12, 8
	s_abs_i32 s12, s33
	v_cvt_f32_u32_e32 v2, s12
	s_mul_i32 s82, s82, s31
	s_sub_i32 s42, s79, s82
	s_sub_i32 s82, 0, s12
	v_rcp_iflag_f32_e32 v2, v2
	s_abs_i32 s79, s42
	s_xor_b32 s43, s42, s33
	s_ashr_i32 s43, s43, 31
	v_mul_f32_e32 v2, 0x4f7ffffe, v2
	v_cvt_u32_f32_e32 v2, v2
	s_nop 0
	v_readfirstlane_b32 s83, v2
	s_mul_i32 s82, s82, s83
	s_mul_hi_u32 s82, s83, s82
	s_add_i32 s83, s83, s82
	s_mul_hi_u32 s82, s79, s83
	s_mul_i32 s83, s82, s12
	s_sub_i32 s79, s79, s83
	s_add_i32 s94, s82, 1
	s_sub_i32 s83, s79, s12
	s_cmp_ge_u32 s79, s12
	s_cselect_b32 s82, s94, s82
	s_cselect_b32 s79, s83, s79
	s_add_i32 s83, s82, 1
	s_cmp_ge_u32 s79, s12
	s_cselect_b32 s12, s83, s82
	s_xor_b32 s12, s12, s43
	s_sub_i32 s12, s12, s43
	s_mul_i32 s33, s12, s33
	s_sub_i32 s33, s42, s33
	s_add_i32 s33, s33, s24
	s_mov_b64 s[42:43], 0
